# t20 + forget-logit stores written through (sc0 sc1), no L2 write-back at the end of the in-proj phase on the barrier-free path
# baseline (speedup 1.0000x reference)
.LBB0_306:
	s_and_b64 vcc, exec, s[44:45]
	s_cbranch_vccz .LBB0_314
	s_and_saveexec_b64 s[0:1], s[46:47]
	s_cbranch_execz .LBB0_309
	v_ashrrev_i32_e32 v151, 31, v150
	s_waitcnt lgkmcnt(0)
	v_lshl_add_u64 v[152:153], v[150:151], 2, s[66:67]
	global_load_dword v162, v[152:153], off
	v_lshlrev_b64 v[154:155], 5, v[150:151]
	v_lshl_add_u64 v[154:155], s[30:31], 0, v[154:155]
	s_mov_b64 s[2:3], 0x1000
	s_waitcnt vmcnt(0)
	v_pk_mul_f32 v[158:159], v[126:127], v[162:163] op_sel_hi:[1,0]
	v_pk_mul_f32 v[156:157], v[124:125], v[162:163] op_sel_hi:[1,0]
	global_store_dwordx4 v[154:155], v[156:159], off sc0 sc1
	s_nop 1
	v_pk_mul_f32 v[158:159], v[122:123], v[162:163] op_sel_hi:[1,0]
	v_pk_mul_f32 v[156:157], v[120:121], v[162:163] op_sel_hi:[1,0]
	global_store_dwordx4 v[154:155], v[156:159], off offset:16 sc0 sc1
	global_load_dword v164, v[152:153], off offset:64
	v_or_b32_e32 v162, 16, v150
	v_ashrrev_i32_e32 v163, 31, v162
	v_lshlrev_b64 v[162:163], 5, v[162:163]
	v_lshl_add_u64 v[162:163], s[30:31], 0, v[162:163]
	s_waitcnt vmcnt(0)
	v_pk_mul_f32 v[158:159], v[110:111], v[164:165] op_sel_hi:[1,0]
	v_pk_mul_f32 v[156:157], v[108:109], v[164:165] op_sel_hi:[1,0]
	global_store_dwordx4 v[162:163], v[156:159], off sc0 sc1
	s_nop 1
	v_pk_mul_f32 v[158:159], v[106:107], v[164:165] op_sel_hi:[1,0]
	v_pk_mul_f32 v[156:157], v[104:105], v[164:165] op_sel_hi:[1,0]
	global_store_dwordx4 v[162:163], v[156:159], off offset:16 sc0 sc1
	global_load_dword v164, v[152:153], off offset:128
	v_or_b32_e32 v162, 32, v150
	v_ashrrev_i32_e32 v163, 31, v162
	v_lshlrev_b64 v[162:163], 5, v[162:163]
	v_lshl_add_u64 v[162:163], s[30:31], 0, v[162:163]
	s_waitcnt vmcnt(0)
	v_pk_mul_f32 v[158:159], v[94:95], v[164:165] op_sel_hi:[1,0]
	v_pk_mul_f32 v[156:157], v[92:93], v[164:165] op_sel_hi:[1,0]
	global_store_dwordx4 v[162:163], v[156:159], off sc0 sc1
	s_nop 1
	v_pk_mul_f32 v[158:159], v[90:91], v[164:165] op_sel_hi:[1,0]
	v_pk_mul_f32 v[156:157], v[88:89], v[164:165] op_sel_hi:[1,0]
	global_store_dwordx4 v[162:163], v[156:159], off offset:16 sc0 sc1
	global_load_dword v164, v[152:153], off offset:192
	v_or_b32_e32 v162, 48, v150
	v_ashrrev_i32_e32 v163, 31, v162
	v_lshlrev_b64 v[162:163], 5, v[162:163]
	v_lshl_add_u64 v[162:163], s[30:31], 0, v[162:163]
	s_waitcnt vmcnt(0)
	v_pk_mul_f32 v[158:159], v[78:79], v[164:165] op_sel_hi:[1,0]
	v_pk_mul_f32 v[156:157], v[76:77], v[164:165] op_sel_hi:[1,0]
	global_store_dwordx4 v[162:163], v[156:159], off sc0 sc1
	s_nop 1
	v_pk_mul_f32 v[158:159], v[74:75], v[164:165] op_sel_hi:[1,0]
	v_pk_mul_f32 v[156:157], v[72:73], v[164:165] op_sel_hi:[1,0]
	global_store_dwordx4 v[162:163], v[156:159], off offset:16 sc0 sc1
	global_load_dword v162, v[152:153], off offset:512
	v_lshl_add_u64 v[164:165], v[154:155], 0, s[2:3]
	s_movk_i32 s2, 0x1000
	v_add_co_u32_e32 v166, vcc, s2, v154
	s_mov_b64 s[2:3], 0x1200
	s_nop 0
	v_addc_co_u32_e32 v167, vcc, 0, v155, vcc
	s_waitcnt vmcnt(0)
	v_pk_mul_f32 v[158:159], v[62:63], v[162:163] op_sel_hi:[1,0]
	v_pk_mul_f32 v[156:157], v[60:61], v[162:163] op_sel_hi:[1,0]
	global_store_dwordx4 v[166:167], v[156:159], off sc0 sc1
	s_nop 1
	v_pk_mul_f32 v[158:159], v[58:59], v[162:163] op_sel_hi:[1,0]
	v_pk_mul_f32 v[156:157], v[56:57], v[162:163] op_sel_hi:[1,0]
	global_store_dwordx4 v[164:165], v[156:159], off offset:16 sc0 sc1
	global_load_dword v162, v[152:153], off offset:576
	v_lshl_add_u64 v[164:165], v[154:155], 0, s[2:3]
	s_mov_b64 s[2:3], 0x1400
	s_waitcnt vmcnt(0)
	v_pk_mul_f32 v[158:159], v[46:47], v[162:163] op_sel_hi:[1,0]
	v_pk_mul_f32 v[156:157], v[44:45], v[162:163] op_sel_hi:[1,0]
	global_store_dwordx4 v[166:167], v[156:159], off offset:512 sc0 sc1
	s_nop 1
	v_pk_mul_f32 v[158:159], v[42:43], v[162:163] op_sel_hi:[1,0]
	v_pk_mul_f32 v[156:157], v[40:41], v[162:163] op_sel_hi:[1,0]
	global_store_dwordx4 v[164:165], v[156:159], off offset:16 sc0 sc1
	global_load_dword v162, v[152:153], off offset:640
	v_lshl_add_u64 v[164:165], v[154:155], 0, s[2:3]
	s_mov_b64 s[2:3], 0x1600
	s_waitcnt vmcnt(0)
	v_pk_mul_f32 v[158:159], v[30:31], v[162:163] op_sel_hi:[1,0]
	v_pk_mul_f32 v[156:157], v[28:29], v[162:163] op_sel_hi:[1,0]
	global_store_dwordx4 v[166:167], v[156:159], off offset:1024 sc0 sc1
	s_nop 1
	v_pk_mul_f32 v[158:159], v[26:27], v[162:163] op_sel_hi:[1,0]
	v_pk_mul_f32 v[156:157], v[24:25], v[162:163] op_sel_hi:[1,0]
	global_store_dwordx4 v[164:165], v[156:159], off offset:16 sc0 sc1
	global_load_dword v152, v[152:153], off offset:704
	v_lshl_add_u64 v[162:163], v[154:155], 0, s[2:3]
	s_waitcnt vmcnt(0)
	v_pk_mul_f32 v[158:159], v[14:15], v[152:153] op_sel_hi:[1,0]
	v_pk_mul_f32 v[156:157], v[12:13], v[152:153] op_sel_hi:[1,0]
	v_pk_mul_f32 v[154:155], v[10:11], v[152:153] op_sel_hi:[1,0]
	v_pk_mul_f32 v[152:153], v[8:9], v[152:153] op_sel_hi:[1,0]
	global_store_dwordx4 v[166:167], v[156:159], off offset:1536 sc0 sc1
	global_store_dwordx4 v[162:163], v[152:155], off offset:16 sc0 sc1

.LBB0_317:
	s_cmp_gt_i32 s71, 2
	s_cselect_b64 s[0:1], -1, 0
	s_and_b64 s[2:3], s[34:35], s[0:1]
	s_andn2_b64 vcc, exec, s[2:3]
	s_cbranch_vccnz .LBB0_371
	s_cmpk_lg_i32 s92, 0x100
	s_cbranch_scc1 .Lsyn_drain
	s_branch .Lsyn_nodrain

.Lsyn_nodrain:
	v_cmp_eq_u32_e32 vcc, 0, v161
	s_and_saveexec_b64 s[2:3], vcc
	s_cbranch_execz .Lsyn_pub_done
	s_cmpk_lg_i32 s92, 0x100
	s_cbranch_scc1 .Lsyn_dowb
	s_branch .Lsyn_nowb
